# dead-work elimination: pre-pass skips the bf16 state-image LDS stores (only the full pass reads that image)
# baseline (speedup 1.0000x reference)
; #define MFMA(a, b, c) __builtin_amdgcn_mfma_f32_32x32x16_bf16((a), (b), (c), 0, 0, 0)
; DI unsigned pk2(float lo, float hi) { f32x2 v = {lo, hi}; bf2_t r = __builtin_convertvector(v, bf2_t); return __builtin_bit_cast(unsigned, r); }
; DI void ssd_scan_phase(bf16_t* P, const bf16_t* BT, const bf16_t* Cc, const bf16_t* CB, const float* dt, const float* acs,
;                        const float* cw, const float* cb, const float* Dp, char* lds, bool dry, int mode, float* Sbuf) {
;     ...
;         const int nt = wave - 4;
;         const float dec = __expf(cAcs[127]);
; #pragma unroll
;         for (int i = 0; i < 16; ++i) st[i] *= dec;
; #pragma unroll
;         for (int kk = 0; kk < 8; ++kk) {
;           const bf16x8 xf = *(const bf16x8*)(sBT + swz128(32 * nt + lq, 2 * kk + hq));
;           const bf16x8 yf = *(const bf16x8*)(sXds + swz128(lq, 2 * kk + hq));
;           st = MFMA(xf, yf, st);
;         }
;         char* stn = sSt + ((c + 1) & 1) * 8192;
; #pragma unroll
;         for (int gi = 0; gi < 4; ++gi) {
;           u32x2 ov; ov[0] = pk2(st[4 * gi], st[4 * gi + 1]); ov[1] = pk2(st[4 * gi + 2], st[4 * gi + 3]);
;           *(u32x2*)(stn + l31 * 256 + (((4 * nt + gi) ^ (l31 & 15)) << 4) + 8 * h) = ov;
;         }
.LBB0_1106:
.LBB0_1107:
	s_andn2_saveexec_b64 s[80:81], s[80:81]
	s_cbranch_execz .LBB0_1109
	v_mov_b32_e32 v20, s88
	ds_read_b32 v250, v20 offset:508
	s_add_i32 s82, 0, 0x1a000
	v_lshlrev_b32_e32 v20, 8, v174
	v_add_u32_e32 v28, v186, v20
	v_add_u32_e32 v29, s82, v20
	v_bitop3_b32 v20, v174, v197, 15 bitop3:0x6c
	v_lshlrev_b32_e32 v24, 4, v20
	v_add_u32_e32 v251, v28, v24
	v_add_u32_e32 v231, v29, v24
	s_and_b32 s82, s85, 0x2000
	ds_read_b128 v[20:23], v251
	ds_read_b128 v[24:27], v231
	v_xor_b32_e32 v230, 0x20, v251
	ds_read_b128 v[28:31], v230
	v_xor_b32_e32 v230, 0x20, v231
	ds_read_b128 v[32:35], v230
	v_xor_b32_e32 v230, 0x40, v251
	ds_read_b128 v[36:39], v230
	v_xor_b32_e32 v230, 0x40, v231
	ds_read_b128 v[40:43], v230
	v_xor_b32_e32 v230, 0x60, v251
	ds_read_b128 v[44:47], v230
	v_xor_b32_e32 v230, 0x60, v231
	ds_read_b128 v[48:51], v230
	v_xor_b32_e32 v230, 0x80, v251
	ds_read_b128 v[222:225], v230
	v_xor_b32_e32 v230, 0x80, v231
	ds_read_b128 v[226:229], v230
	v_xor_b32_e32 v230, 0xa0, v251
	ds_read_b128 v[234:237], v230
	v_xor_b32_e32 v230, 0xa0, v231
	ds_read_b128 v[238:241], v230
	v_xor_b32_e32 v230, 0xc0, v251
	ds_read_b128 v[242:245], v230
	v_xor_b32_e32 v230, 0xc0, v231
	ds_read_b128 v[246:249], v230
	s_waitcnt lgkmcnt(14)
	v_mul_f32_e32 v250, 0x3fb8aa3b, v250
	v_exp_f32_e32 v250, v250
	s_nop 0
	v_pk_mul_f32 v[18:19], v[18:19], v[250:251] op_sel_hi:[1,0]
	v_pk_mul_f32 v[16:17], v[16:17], v[250:251] op_sel_hi:[1,0]
	v_pk_mul_f32 v[14:15], v[14:15], v[250:251] op_sel_hi:[1,0]
	v_pk_mul_f32 v[12:13], v[12:13], v[250:251] op_sel_hi:[1,0]
	v_pk_mul_f32 v[10:11], v[10:11], v[250:251] op_sel_hi:[1,0]
	v_pk_mul_f32 v[8:9], v[8:9], v[250:251] op_sel_hi:[1,0]
	v_pk_mul_f32 v[6:7], v[6:7], v[250:251] op_sel_hi:[1,0]
	v_pk_mul_f32 v[4:5], v[4:5], v[250:251] op_sel_hi:[1,0]
	s_nop 1
	s_waitcnt lgkmcnt(12)
	v_mfma_f32_32x32x16_bf16 v[4:19], v[20:23], v[24:27], v[4:19]
	v_xor_b32_e32 v230, 0xe0, v251
	ds_read_b128 v[20:23], v230
	v_xor_b32_e32 v230, 0xe0, v231
	ds_read_b128 v[24:27], v230
	s_waitcnt lgkmcnt(12)
	v_mfma_f32_32x32x16_bf16 v[4:19], v[28:31], v[32:35], v[4:19]
	s_waitcnt lgkmcnt(10)
	v_mfma_f32_32x32x16_bf16 v[4:19], v[36:39], v[40:43], v[4:19]
	s_waitcnt lgkmcnt(8)
	v_mfma_f32_32x32x16_bf16 v[4:19], v[44:47], v[48:51], v[4:19]
	s_waitcnt lgkmcnt(6)
	v_mfma_f32_32x32x16_bf16 v[4:19], v[222:225], v[226:229], v[4:19]
	s_waitcnt lgkmcnt(4)
	v_mfma_f32_32x32x16_bf16 v[4:19], v[234:237], v[238:241], v[4:19]
	s_waitcnt lgkmcnt(2)
	v_mfma_f32_32x32x16_bf16 v[4:19], v[242:245], v[246:249], v[4:19]
	s_waitcnt lgkmcnt(0)
	v_mfma_f32_32x32x16_bf16 v[4:19], v[20:23], v[24:27], v[4:19]
	s_cmp_lg_u64 s[56:57], 0
	s_cbranch_scc1 .LBB0_1109
	v_add_u32_e32 v22, s82, v180
	v_add_u32_e32 v23, v22, v121
	s_nop 9
	v_cvt_pk_bf16_f32 v20, v4, v5
	v_cvt_pk_bf16_f32 v21, v6, v7
	ds_write_b64 v23, v[20:21]
	v_cvt_pk_bf16_f32 v20, v8, v9
	v_cvt_pk_bf16_f32 v21, v10, v11
	v_add_u32_e32 v23, v22, v188
	ds_write_b64 v23, v[20:21]
	v_cvt_pk_bf16_f32 v20, v12, v13
	v_cvt_pk_bf16_f32 v21, v14, v15
	v_add_u32_e32 v23, v22, v189
	ds_write_b64 v23, v[20:21]
	v_cvt_pk_bf16_f32 v20, v16, v17
	v_cvt_pk_bf16_f32 v21, v18, v19
	v_add_u32_e32 v22, v22, v190
	ds_write_b64 v22, v[20:21]
